# v11 plus P3 prompt in-projection on 224 WGs (exactly 6 units each), 24 quota-copier WGs
# speedup vs baseline: 1.0038x; 1.0038x over previous
; #define GEMM(EPI, Aop, Bop, Nn, Kk, nM_, pmoff, Gs, cs, Eobj) do { pg8::Gemm g_{Aop, Bop, T, Nn, Kk}; pg8::SubOrder S_; S_.init(nM_, (Nn) / 256, pmoff, Gs, cs); \
;         pg8::gemm_phase<EPI, pg8::SubOrder, true, true>(lds, g_, S_, Eobj); } while (0)
;     __host__ __device__ bool next(int i, Unit& u) const {
;         const long L = (long)i * G + c; if (c < 0 || L >= nwg) return false;
;         int wgid = (int)L; { const int q = nwg / NXCD, r = nwg % NXCD, xcd = wgid % NXCD, off = wgid / NXCD; wgid = (xcd < r ? xcd * (q + 1) : r * (q + 1) + (xcd - r) * q) + off; }
;         const int nig = WGM * nN, gid = wgid / nig, fm = gid * WGM, gsz = (nM - fm) < WGM ? (nM - fm) : WGM;
;         u.pm = pm_off + fm + ((wgid % nig) % gsz); u.pn = (wgid % nig) / gsz; return true;
; __global__ void __launch_bounds__(512, 2) mk_fwd(Args args) {
;     ...
;     if (IN(3)) {
;         { pg8::EpiIn E{rss1, Ub, Qb, Gb, args.in[14], (const float*)(ws + WS_QKN), (const float*)(ws + WS_ROT), args.out};
;           GEMM(pg8::EpiIn, X1B, W3, NIN, D, 64, 0, G - 24, bid < G - 24 ? bid : -1, E); }
.LBB0_375:
	v_writelane_b32 v250, s60, 5
	s_cmp_lt_i32 s82, 4
	s_cselect_b64 s[0:1], -1, 0
	v_writelane_b32 v250, s61, 6
	v_writelane_b32 v250, s89, 7
	v_writelane_b32 v250, s58, 8
	s_add_u32 s4, s80, 0x10e3b100
	s_addc_u32 s5, s81, 0
	v_writelane_b32 v250, s59, 9
	v_writelane_b32 v250, s4, 10
	s_nop 1
	v_writelane_b32 v250, s5, 11
	s_add_u32 s4, s80, 0x11ebb100
	s_addc_u32 s5, s81, 0
	s_add_u32 s94, s80, 0x168fb100
	s_addc_u32 s95, s81, 0
	s_and_b64 s[44:45], s[0:1], s[2:3]
	v_writelane_b32 v250, s4, 12
	s_andn2_b64 vcc, exec, s[44:45]
	s_nop 0
	v_writelane_b32 v250, s5, 13
	s_cbranch_vccnz .LBB0_961
	v_readlane_b32 s0, v250, 8
	s_sub_i32 s72, s0, 32
	s_cmp_ge_i32 s96, s72
	v_readlane_b32 s1, v250, 9
	s_cselect_b64 s[52:53], -1, 0
	s_and_b64 s[0:1], s[52:53], exec
	s_cselect_b32 s27, -1, s96
	s_cmp_gt_i32 s27, -1
	s_cselect_b64 s[2:3], -1, 0
	s_cmp_lt_i32 s27, s72
	s_cselect_b64 s[0:1], -1, 0
	s_and_b64 s[0:1], s[2:3], s[0:1]
	s_and_b64 s[0:1], s[0:1], exec
	s_cselect_b32 s0, 0x540, 0
	s_cmp_lt_u32 s27, s0
	s_cselect_b64 s[4:5], -1, 0
	s_and_b64 s[2:3], s[2:3], s[4:5]
	s_waitcnt vmcnt(0)
	v_mov_b32_e32 v10, v0
	v_cndmask_b32_e64 v2, 0, 1, s[2:3]
	v_cmp_ne_u32_e64 s[6:7], 1, v2
	s_andn2_b64 vcc, exec, s[2:3]
	v_readfirstlane_b32 s8, v10
	s_cbranch_vccnz .LBB0_378
	s_lshr_b32 s1, s0, 3
	s_and_b32 s2, s27, 7
	s_lshr_b32 s3, s27, 3
	s_mul_i32 s1, s1, s2
	s_add_i32 s1, s1, s3
	s_bfe_u32 s2, s1, 0xd0003
	s_mulk_i32 s2, 0xc31
	s_lshr_b32 s2, s2, 16
	s_lshl_b32 s3, s2, 3
	s_mulk_i32 s2, 0xa8
	s_sub_i32 s1, s1, s2
	s_and_b32 s2, s1, 7
	s_or_b32 s2, s2, s3
	s_and_b32 s2, s2, 0x7fff
	s_bfe_u32 s38, s1, 0xd0003

; __global__ void __launch_bounds__(512, 2) mk_fwd(Args args) {
;     ...
;         if (bid >= G - 24) {
;             unsigned* cnt = fctl + 64 * 26;
;             if (bid >= G - 8) { __threadfence(); __syncthreads(); if (tid == 0) __hip_atomic_fetch_add(cnt, 1u, __ATOMIC_RELEASE, __HIP_MEMORY_SCOPE_AGENT); }
;             if (tid == 0) { unsigned sp = 0; while (__hip_atomic_load(cnt, __ATOMIC_ACQUIRE, __HIP_MEMORY_SCOPE_AGENT) < 8u) { __builtin_amdgcn_s_sleep(8); if (++sp > (1u << 22)) break; } }
;             __syncthreads(); __threadfence();
.LBB0_711:
	v_readlane_b32 s72, v250, 8
	s_sub_i32 s72, s72, 24
	s_cmp_ge_i32 s96, s72
	s_cselect_b64 s[52:53], -1, 0
	s_andn2_b64 vcc, exec, s[52:53]
	s_cbranch_vccnz .LBB0_961
	s_add_u32 s2, s80, 0x5a00
	s_addc_u32 s3, s81, 0
	s_andn2_b64 vcc, exec, s[0:1]
	s_mov_b64 s[4:5], -1
	s_cbranch_vccnz .LBB0_718
	v_cmp_eq_u32_e32 vcc, 0, v0
	s_mov_b64 s[4:5], 0
	buffer_wbl2 sc1
	s_waitcnt vmcnt(0) lgkmcnt(0)
	buffer_inv sc1
	s_barrier
	s_and_saveexec_b64 s[0:1], vcc
	s_cbranch_execz .LBB0_717
	s_mov_b64 s[6:7], exec
	v_mbcnt_lo_u32_b32 v2, s6, 0
	v_mbcnt_hi_u32_b32 v2, s7, v2
	v_cmp_eq_u32_e32 vcc, 0, v2
	s_and_saveexec_b64 s[4:5], vcc
	s_cbranch_execz .LBB0_716
	s_bcnt1_i32_b64 s6, s[6:7]
	v_mov_b32_e32 v2, 0
	v_mov_b32_e32 v3, s6
	buffer_wbl2 sc1
	global_atomic_add v2, v3, s[2:3]
